# rwkv_prep raw-row loads issued back-to-back (was load-wait-store x5), on top of K-loop reschedule and scan rewrite
# speedup vs baseline: 1.0177x; 1.0026x over previous
; DI u16 f2bf(float a) { return (u16)(pack2(a, 0.f) & 0xffffu); }
; #define SHIFTED(tt, c, MP, MN) ({ float x_ = bf2f(raw[((tt) + 1) * 1024 + (c)]); float xp_ = bf2f(raw[(tt) * 1024 + (c)]); \
;                           float xn_ = bf2f(raw[((tt) + 2) * 1024 + (c)]); x_ + (MP) * (xp_ - x_) + (MN) * (xn_ - x_); })
; DI void rwkv_prep_group(const Params& p, int l, int grp, char* smem) {
;     ...
;   const int mh0 = grp * 8, bb = mh0 / T, t0 = mh0 % T;
;   const int lo = t0 < 256 ? 0 : 256, hi = t0 < 256 ? 256 : T;
;   __syncthreads();
; #pragma unroll
;   for (int i = 0; i < 5; i++) {
;     int c = tid + i * 256;
;     int rr = c >> 7, ch = c & 127;
;     int t = t0 - 1 + rr;
;     u32x4 w = u32x4{0, 0, 0, 0};
;     if (t >= lo && t < hi) w = *(const u32x4*)(p.P + ((long)bb * T + t) * NP1 + C_SH + ch * 8);
;     *(u32x4*)(raw + rr * 1024 + ch * 8) = w;
;   }
;   __syncthreads();
;   const float* mup = p.in[11] + (long)l * 2 * 1024;
;   const float* mun = mup + 1024;
;   const float mp0 = mup[tid], mn0 = mun[tid], mp1 = mup[256 + tid], mn1 = mun[256 + tid];
;   const float mp2 = mup[512 + tid], mn2 = mun[512 + tid], mp3 = mup[768 + tid], mn3 = mun[768 + tid];
;     ...
;   u16* Abf = (u16*)lora;
;   float* zacc = (float*)(smem + 10 * 1024 * 2 + 32 * 264 * 2);
;   {
;     int c = 768 + tid;
; #pragma unroll
;     for (int tt = 0; tt < 8; tt++) {
;       float s = SHIFTED(tt, c, mp3, mn3);
;       if (tid < 128) s = tanhf(s);
;       Abf[tt * 264 + tid] = f2bf(s);
;     }
;   }
.LBB0_879:
	s_andn2_b64 vcc, exec, s[0:1]
	s_cbranch_vccnz .LBB0_413
	s_mul_hi_i32 s1, s68, 0x78787879
	s_lshl_b32 s0, s68, 3
	s_lshr_b32 s12, s1, 31
	s_ashr_i32 s1, s1, 8
	s_add_i32 s12, s1, s12
	s_mul_hi_i32 s1, s0, 0x78787879
	s_lshr_b32 s13, s1, 31
	s_ashr_i32 s1, s1, 11
	s_add_i32 s1, s1, s13
	s_mulk_i32 s1, 0x1100
	s_sub_i32 s38, s0, s1
	s_cmpk_lt_i32 s38, 0x100
	s_movk_i32 s0, 0x1100
	v_mov_b32 v36, v198
	s_cselect_b32 s13, 0, 0x100
	s_cselect_b32 s21, 0x100, s0
	s_add_i32 s26, s38, -1
	s_waitcnt vmcnt(1)
	v_ashrrev_i32_e32 v9, 7, v36
	v_and_b32_e32 v1, 0x7f, v36
	v_add_u32_e32 v176, s26, v9
	v_lshlrev_b32_e32 v2, 3, v1
	v_cmp_le_i32_e32 vcc, s13, v176
	v_cmp_gt_i32_e64 s[0:1], s21, v176
	s_mul_hi_i32 s37, s12, 0x1100
	s_mul_i32 s36, s12, 0x1100
	s_and_b64 s[48:49], vcc, s[0:1]
	v_mov_b32_e32 v0, 0
	v_lshlrev_b32_e32 v6, 1, v2
	v_mov_b32_e32 v2, 0
	v_mov_b32_e32 v3, 0
	v_mov_b32_e32 v4, 0
	v_mov_b32_e32 v5, 0
	s_barrier
	v_readlane_b32 s54, v255, 11
	v_readlane_b32 s55, v255, 12
	v_lshlrev_b32_e32 v8, 4, v1
	v_lshl_or_b32 v1, v9, 11, v8
	v_mov_b32_e32 v7, v177
	v_mov_b32_e32 v12, 0
	v_mov_b32_e32 v13, 0
	v_mov_b32_e32 v14, 0
	v_mov_b32_e32 v15, 0
	s_and_saveexec_b64 s[0:1], s[48:49]
	s_cbranch_execz .Lrw_skip0
	v_lshl_add_u64 v[32:33], s[36:37], 0, v[176:177]
	v_mov_b64_e32 v[34:35], s[54:55]
	v_mad_u64_u32 v[34:35], s[48:49], v32, s25, v[34:35]
	v_mov_b32_e32 v32, v35
	v_mad_u64_u32 v[32:33], s[48:49], v33, s25, v[32:33]
	v_mov_b32_e32 v35, v32
	v_lshl_add_u64 v[32:33], v[34:35], 0, v[6:7]
	global_load_dwordx4 v[12:15], v[32:33], off offset:1536
.Lrw_skip0:
	s_or_b64 exec, exec, s[0:1]
	v_add_u32_e32 v176, 2, v9
	v_add_u32_e32 v176, s26, v176
	v_cmp_le_i32_e32 vcc, s13, v176
	v_cmp_gt_i32_e64 s[0:1], s21, v176
	s_and_b64 s[48:49], vcc, s[0:1]
	v_mov_b32_e32 v16, 0
	v_mov_b32_e32 v17, 0
	v_mov_b32_e32 v18, 0
	v_mov_b32_e32 v19, 0
	s_and_saveexec_b64 s[0:1], s[48:49]
	s_cbranch_execz .Lrw_skip1
	v_lshl_add_u64 v[32:33], s[36:37], 0, v[176:177]
	v_mov_b64_e32 v[34:35], s[54:55]
	v_mad_u64_u32 v[34:35], s[48:49], v32, s25, v[34:35]
	v_mov_b32_e32 v32, v35
	v_mad_u64_u32 v[32:33], s[48:49], v33, s25, v[32:33]
	v_mov_b32_e32 v35, v32
	v_lshl_add_u64 v[32:33], v[34:35], 0, v[6:7]
	global_load_dwordx4 v[16:19], v[32:33], off offset:1536
.Lrw_skip1:
	s_or_b64 exec, exec, s[0:1]
	v_add_u32_e32 v176, 4, v9
	v_add_u32_e32 v176, s26, v176
	v_cmp_le_i32_e32 vcc, s13, v176
	v_cmp_gt_i32_e64 s[0:1], s21, v176
	s_and_b64 s[48:49], vcc, s[0:1]
	v_mov_b32_e32 v20, 0
	v_mov_b32_e32 v21, 0
	v_mov_b32_e32 v22, 0
	v_mov_b32_e32 v23, 0
	s_and_saveexec_b64 s[0:1], s[48:49]
	s_cbranch_execz .Lrw_skip2
	v_lshl_add_u64 v[32:33], s[36:37], 0, v[176:177]
	v_mov_b64_e32 v[34:35], s[54:55]
	v_mad_u64_u32 v[34:35], s[48:49], v32, s25, v[34:35]
	v_mov_b32_e32 v32, v35
	v_mad_u64_u32 v[32:33], s[48:49], v33, s25, v[32:33]
	v_mov_b32_e32 v35, v32
	v_lshl_add_u64 v[32:33], v[34:35], 0, v[6:7]
	global_load_dwordx4 v[20:23], v[32:33], off offset:1536
.Lrw_skip2:
	s_or_b64 exec, exec, s[0:1]
	v_add_u32_e32 v176, 6, v9
	v_add_u32_e32 v176, s26, v176
	v_cmp_le_i32_e32 vcc, s13, v176
	v_cmp_gt_i32_e64 s[0:1], s21, v176
	s_and_b64 s[48:49], vcc, s[0:1]
	v_mov_b32_e32 v24, 0
	v_mov_b32_e32 v25, 0
	v_mov_b32_e32 v26, 0
	v_mov_b32_e32 v27, 0
	s_and_saveexec_b64 s[0:1], s[48:49]
	s_cbranch_execz .Lrw_skip3
	v_lshl_add_u64 v[32:33], s[36:37], 0, v[176:177]
	v_mov_b64_e32 v[34:35], s[54:55]
	v_mad_u64_u32 v[34:35], s[48:49], v32, s25, v[34:35]
	v_mov_b32_e32 v32, v35
	v_mad_u64_u32 v[32:33], s[48:49], v33, s25, v[32:33]
	v_mov_b32_e32 v35, v32
	v_lshl_add_u64 v[32:33], v[34:35], 0, v[6:7]
	global_load_dwordx4 v[24:27], v[32:33], off offset:1536
.Lrw_skip3:
	s_or_b64 exec, exec, s[0:1]
	v_add_u32_e32 v176, 8, v9
	v_add_u32_e32 v176, s26, v176
	v_cmp_le_i32_e32 vcc, s13, v176
	v_cmp_gt_i32_e64 s[0:1], s21, v176
	s_and_b64 s[48:49], vcc, s[0:1]
	v_mov_b32_e32 v28, 0
	v_mov_b32_e32 v29, 0
	v_mov_b32_e32 v30, 0
	v_mov_b32_e32 v31, 0
	s_and_saveexec_b64 s[0:1], s[48:49]
	s_cbranch_execz .Lrw_skip4
	v_lshl_add_u64 v[32:33], s[36:37], 0, v[176:177]
	v_mov_b64_e32 v[34:35], s[54:55]
	v_mad_u64_u32 v[34:35], s[48:49], v32, s25, v[34:35]
	v_mov_b32_e32 v32, v35
	v_mad_u64_u32 v[32:33], s[48:49], v33, s25, v[32:33]
	v_mov_b32_e32 v35, v32
	v_lshl_add_u64 v[32:33], v[34:35], 0, v[6:7]
	global_load_dwordx4 v[28:31], v[32:33], off offset:1536
.Lrw_skip4:
	s_or_b64 exec, exec, s[0:1]
	s_waitcnt vmcnt(3)
	ds_write_b128 v1, v[12:15]
	s_waitcnt vmcnt(2)
	ds_write_b128 v1, v[16:19] offset:4096
	s_waitcnt vmcnt(1)
	ds_write_b128 v1, v[20:23] offset:8192
	s_waitcnt vmcnt(0)
	ds_write_b128 v1, v[24:27] offset:12288
	s_waitcnt vmcnt(0)
	ds_write_b128 v1, v[28:31] offset:16384
	v_ashrrev_i32_e32 v37, 31, v36
	v_readlane_b32 s0, v255, 28
	v_lshlrev_b64 v[0:1], 2, v[36:37]
	v_readlane_b32 s1, v255, 29
	s_waitcnt lgkmcnt(0)
	s_barrier
	v_lshl_add_u64 v[2:3], s[0:1], 0, v[0:1]
	v_readlane_b32 s0, v255, 30
	v_readlane_b32 s1, v255, 31
	v_lshlrev_b32_e32 v53, 1, v36
	s_nop 0
	v_lshl_add_u64 v[0:1], s[0:1], 0, v[0:1]
	global_load_dword v40, v[0:1], off
	global_load_dword v43, v[0:1], off offset:1024
	global_load_dword v41, v[0:1], off offset:2048
	s_nop 0
	global_load_dword v1, v[0:1], off offset:3072
	s_nop 0
	global_load_dword v0, v[2:3], off offset:3072
	global_load_dword v45, v[2:3], off
	global_load_dword v44, v[2:3], off offset:1024
	global_load_dword v42, v[2:3], off offset:2048
	ds_read_u16 v2, v53 offset:3584
	ds_read_u16 v3, v53 offset:5632
	ds_read_u16 v4, v53 offset:1536
	s_movk_i32 s0, 0x80
	v_cmp_gt_i32_e32 vcc, s0, v36
	s_waitcnt lgkmcnt(2)
	v_lshlrev_b32_e32 v2, 16, v2
	s_waitcnt lgkmcnt(1)
	v_lshlrev_b32_e32 v5, 16, v3
	s_waitcnt lgkmcnt(0)
	v_lshlrev_b32_e32 v4, 16, v4
	v_pk_add_f32 v[6:7], v[4:5], v[2:3] op_sel_hi:[1,0] neg_lo:[0,1] neg_hi:[0,1]
	s_waitcnt vmcnt(3)
	v_pk_mul_f32 v[6:7], v[0:1], v[6:7]
	s_nop 0
	v_add_f32_e32 v3, v6, v2
	v_add_f32_e32 v3, v3, v7
	s_and_saveexec_b64 s[48:49], vcc
	s_mov_b32 s13, 0x3f200000
	s_brev_b32 s21, -2
	s_cbranch_execz .LBB0_896
	v_cmp_nlt_f32_e64 s[0:1], |v3|, s13
	s_and_saveexec_b64 s[50:51], s[0:1]
	s_xor_b64 s[50:51], exec, s[50:51]
	s_cbranch_execz .LBB0_893
	v_add_f32_e64 v6, |v3|, |v3|
	v_mul_f32_e32 v7, 0x3fb8aa3b, v6
	v_rndne_f32_e32 v8, v7
	s_mov_b32 s0, 0x3fb8aa3b
	v_sub_f32_e32 v9, v7, v8
	v_fma_f32 v7, v6, s0, -v7
	v_fmac_f32_e32 v7, 0x32a5705f, v6
	v_add_f32_e32 v7, v9, v7
	v_cvt_i32_f32_e32 v8, v8
	v_exp_f32_e32 v7, v7
	s_mov_b32 s0, 0xc2ce8ed0
	v_cmp_ngt_f32_e64 s[0:1], s0, v6
	v_ldexp_f32 v7, v7, v8
	s_nop 0
	v_cndmask_b32_e64 v7, 0, v7, s[0:1]
	s_mov_b32 s0, 0x42b17218
	v_cmp_nlt_f32_e64 s[0:1], s0, v6
	s_nop 1
	v_cndmask_b32_e64 v6, v215, v7, s[0:1]
	v_add_f32_e32 v6, 1.0, v6
	v_rcp_f32_e32 v6, v6
	s_nop 0
	v_fma_f32 v6, v6, -2.0, 1.0
